# c19 + phase 9 sample-token final norm: the four gain loads issued up front, four stores back to back (was a load/wait/store ladder at the kernel's tail)
# baseline (speedup 1.0000x reference)
.LBB0_1760:
	s_or_b64 exec, exec, s[10:11]
	s_andn2_b64 vcc, exec, s[44:45]
	s_waitcnt lgkmcnt(0)
	s_barrier
	s_cbranch_vccnz .LBB0_1757
	s_lshl_b64 s[10:11], s[8:9], 1
	s_add_u32 s10, s24, s10
	v_lshlrev_b32_e32 v0, 8, v12
	s_addc_u32 s11, s25, s11
	v_ashrrev_i32_e32 v1, 31, v0
	v_lshl_add_u64 v[2:3], v[0:1], 1, s[10:11]
	v_lshlrev_b32_e32 v8, 1, v136
	v_lshl_add_u64 v[2:3], v[2:3], 0, v[8:9]
	global_load_dwordx4 v[14:17], v[2:3], off
	global_load_dwordx4 v[18:21], v[2:3], off offset:16
	v_lshlrev_b64 v[6:7], 2, v[0:1]
	v_lshl_add_u64 v[0:1], s[74:75], 0, v[6:7]
	v_lshlrev_b32_e32 v8, 2, v136
	v_lshl_or_b32 v2, v12, 10, v8
	v_lshl_add_u64 v[4:5], v[0:1], 0, v[8:9]
	v_add_u32_e32 v10, 0x10000, v2
	global_load_dwordx4 v[0:3], v[4:5], off
	global_load_dwordx4 v[240:243], v[4:5], off offset:16
	global_load_dwordx4 v[244:247], v[4:5], off offset:32
	global_load_dwordx4 v[248:251], v[4:5], off offset:48
	ds_read_b128 v[22:25], v10
	ds_read_b128 v[26:29], v10 offset:16
	ds_read_b128 v[30:33], v10 offset:32
	ds_read_b128 v[34:37], v10 offset:48
	ds_read_b128 v[38:41], v10 offset:4096
	ds_read_b128 v[42:45], v10 offset:4112
	ds_read_b128 v[46:49], v10 offset:8192
	ds_read_b128 v[50:53], v10 offset:8208
	ds_read_b128 v[54:57], v10 offset:12288
	ds_read_b128 v[58:61], v10 offset:12304
	ds_read_b128 v[62:65], v10 offset:16384
	ds_read_b128 v[66:69], v10 offset:16400
	ds_read_b128 v[70:73], v10 offset:20480
	ds_read_b128 v[74:77], v10 offset:20496
	ds_read_b128 v[78:81], v10 offset:24576
	ds_read_b128 v[82:85], v10 offset:24592
	ds_read_b128 v[86:89], v10 offset:28672
	ds_read_b128 v[90:93], v10 offset:28688
	ds_read_b128 v[94:97], v10 offset:8224
	ds_read_b128 v[98:101], v10 offset:12320
	ds_read_b128 v[102:105], v10 offset:4128
	ds_read_b128 v[106:109], v10 offset:4144
	s_lshl_b64 s[8:9], s[8:9], 2
	s_add_u32 s8, s76, s8
	s_addc_u32 s9, s77, s9
	v_lshl_add_u64 v[6:7], s[8:9], 0, v[6:7]
	v_lshl_add_u64 v[6:7], v[6:7], 0, v[8:9]
	s_waitcnt vmcnt(5)
	v_lshlrev_b32_e32 v12, 16, v14
	v_and_b32_e32 v13, 0xffff0000, v14
	v_lshlrev_b32_e32 v14, 16, v15
	v_and_b32_e32 v15, 0xffff0000, v15
	v_lshlrev_b32_e32 v110, 16, v16
	v_and_b32_e32 v111, 0xffff0000, v16
	v_lshlrev_b32_e32 v16, 16, v17
	v_and_b32_e32 v17, 0xffff0000, v17
	s_waitcnt vmcnt(4)
	v_lshlrev_b32_e32 v112, 16, v18
	v_and_b32_e32 v113, 0xffff0000, v18
	v_lshlrev_b32_e32 v114, 16, v19
	v_and_b32_e32 v115, 0xffff0000, v19
	s_waitcnt lgkmcnt(14)
	v_pk_add_f32 v[12:13], v[22:23], v[12:13]
	v_pk_add_f32 v[14:15], v[24:25], v[14:15]
	v_pk_add_f32 v[18:19], v[26:27], v[110:111]
	v_pk_add_f32 v[16:17], v[28:29], v[16:17]
	v_pk_add_f32 v[12:13], v[12:13], v[38:39]
	v_pk_add_f32 v[14:15], v[14:15], v[40:41]
	v_pk_add_f32 v[18:19], v[18:19], v[42:43]
	v_pk_add_f32 v[16:17], v[16:17], v[44:45]
	v_pk_add_f32 v[12:13], v[12:13], v[46:47]
	v_pk_add_f32 v[14:15], v[14:15], v[48:49]
	v_pk_add_f32 v[18:19], v[18:19], v[50:51]
	v_pk_add_f32 v[16:17], v[16:17], v[52:53]
	s_waitcnt lgkmcnt(13)
	v_pk_add_f32 v[12:13], v[12:13], v[54:55]
	v_pk_add_f32 v[14:15], v[14:15], v[56:57]
	s_waitcnt lgkmcnt(12)
	v_pk_add_f32 v[18:19], v[18:19], v[58:59]
	v_pk_add_f32 v[16:17], v[16:17], v[60:61]
	s_waitcnt lgkmcnt(11)
	v_pk_add_f32 v[12:13], v[12:13], v[62:63]
	v_pk_add_f32 v[14:15], v[14:15], v[64:65]
	s_waitcnt lgkmcnt(10)
	v_pk_add_f32 v[18:19], v[18:19], v[66:67]
	v_pk_add_f32 v[16:17], v[16:17], v[68:69]
	v_lshlrev_b32_e32 v116, 16, v20
	v_and_b32_e32 v117, 0xffff0000, v20
	v_lshlrev_b32_e32 v118, 16, v21
	v_and_b32_e32 v119, 0xffff0000, v21
	v_pk_add_f32 v[20:21], v[30:31], v[112:113]
	s_waitcnt lgkmcnt(9)
	v_pk_add_f32 v[12:13], v[12:13], v[70:71]
	v_pk_add_f32 v[14:15], v[14:15], v[72:73]
	s_waitcnt lgkmcnt(8)
	v_pk_add_f32 v[18:19], v[18:19], v[74:75]
	v_pk_add_f32 v[16:17], v[16:17], v[76:77]
	s_waitcnt lgkmcnt(1)
	v_pk_add_f32 v[20:21], v[20:21], v[102:103]
	v_pk_add_f32 v[12:13], v[12:13], v[78:79]
	v_pk_add_f32 v[14:15], v[14:15], v[80:81]
	v_pk_add_f32 v[18:19], v[18:19], v[82:83]
	v_pk_add_f32 v[16:17], v[16:17], v[84:85]
	v_pk_add_f32 v[58:59], v[12:13], v[86:87]
	v_pk_add_f32 v[60:61], v[14:15], v[88:89]
	v_pk_add_f32 v[62:63], v[18:19], v[90:91]
	v_pk_add_f32 v[64:65], v[16:17], v[92:93]
	ds_read_b128 v[12:15], v10 offset:8240
	v_pk_add_f32 v[24:25], v[20:21], v[94:95]
	ds_read_b128 v[16:19], v10 offset:16416
	ds_read_b128 v[20:23], v10 offset:12336
	v_pk_add_f32 v[38:39], v[24:25], v[98:99]
	ds_read_b128 v[24:27], v10 offset:20512
	ds_read_b128 v[28:31], v10 offset:16432
	v_pk_mul_f32 v[66:67], v[58:59], v[58:59]
	s_waitcnt lgkmcnt(3)
	v_pk_add_f32 v[16:17], v[38:39], v[16:17]
	ds_read_b128 v[38:41], v10 offset:24608
	ds_read_b128 v[42:45], v10 offset:28704
	ds_read_b128 v[46:49], v10 offset:20528
	s_waitcnt lgkmcnt(4)
	v_pk_add_f32 v[16:17], v[16:17], v[24:25]
	v_pk_add_f32 v[24:25], v[32:33], v[114:115]
	ds_read_b128 v[50:53], v10 offset:24624
	ds_read_b128 v[54:57], v10 offset:28720
	v_pk_add_f32 v[24:25], v[24:25], v[104:105]
	s_waitcnt lgkmcnt(4)
	v_pk_add_f32 v[16:17], v[16:17], v[38:39]
	v_pk_add_f32 v[24:25], v[24:25], v[96:97]
	s_waitcnt lgkmcnt(3)
	v_pk_add_f32 v[16:17], v[16:17], v[42:43]
	v_pk_add_f32 v[24:25], v[24:25], v[100:101]
	v_pk_mul_f32 v[70:71], v[62:63], v[62:63]
	v_pk_add_f32 v[18:19], v[24:25], v[18:19]
	v_pk_add_f32 v[24:25], v[34:35], v[116:117]
	v_pk_add_f32 v[18:19], v[18:19], v[26:27]
	v_pk_add_f32 v[24:25], v[24:25], v[106:107]
	v_pk_add_f32 v[18:19], v[18:19], v[40:41]
	v_pk_add_f32 v[12:13], v[24:25], v[12:13]
	v_pk_add_f32 v[18:19], v[18:19], v[44:45]
	v_pk_add_f32 v[12:13], v[12:13], v[20:21]
	v_pk_add_f32 v[20:21], v[36:37], v[118:119]
	v_pk_add_f32 v[12:13], v[12:13], v[28:29]
	v_pk_add_f32 v[20:21], v[20:21], v[108:109]
	s_waitcnt lgkmcnt(2)
	v_pk_add_f32 v[12:13], v[12:13], v[46:47]
	v_pk_add_f32 v[14:15], v[20:21], v[14:15]
	s_waitcnt lgkmcnt(1)
	v_pk_add_f32 v[12:13], v[12:13], v[50:51]
	v_pk_add_f32 v[14:15], v[14:15], v[22:23]
	s_waitcnt lgkmcnt(0)
	v_pk_add_f32 v[12:13], v[12:13], v[54:55]
	v_pk_add_f32 v[14:15], v[14:15], v[30:31]
	v_mov_b32_e32 v22, v17
	v_pk_add_f32 v[14:15], v[14:15], v[48:49]
	v_mov_b32_e32 v23, v13
	v_pk_add_f32 v[14:15], v[14:15], v[52:53]
	v_mov_b32_e32 v20, v16
	v_pk_add_f32 v[14:15], v[14:15], v[56:57]
	v_mov_b32_e32 v21, v12
	v_pk_mul_f32 v[22:23], v[22:23], v[22:23]
	v_pk_mul_f32 v[68:69], v[60:61], v[60:61]
	v_pk_fma_f32 v[20:21], v[20:21], v[20:21], v[22:23]
	v_mov_b32_e32 v22, v18
	v_mov_b32_e32 v23, v14
	v_pk_mul_f32 v[72:73], v[64:65], v[64:65]
	v_pk_fma_f32 v[20:21], v[22:23], v[22:23], v[20:21]
	v_add_f32_e32 v10, v70, v71
	v_add_f32_e32 v22, v66, v67
	v_add_f32_e32 v10, v10, v72
	v_add_f32_e32 v22, v22, v68
	v_mov_b32_e32 v24, v19
	v_mov_b32_e32 v25, v15
	v_add_f32_e32 v10, v10, v73
	v_add_f32_e32 v22, v22, v69
	v_pk_fma_f32 v[20:21], v[24:25], v[24:25], v[20:21]
	v_add_f32_e32 v10, v22, v10
	v_add_f32_e32 v10, v10, v20
	v_add_f32_e32 v10, v10, v21
	s_nop 1
	v_add_f32_dpp v10, v10, v10 quad_perm:[1,0,3,2] row_mask:0xf bank_mask:0xf bound_ctrl:1
	s_nop 1
	v_add_f32_dpp v10, v10, v10 quad_perm:[2,3,0,1] row_mask:0xf bank_mask:0xf bound_ctrl:1
	s_nop 1
	v_add_f32_dpp v10, v10, v10 row_half_mirror row_mask:0xf bank_mask:0xf bound_ctrl:1
	s_nop 1
	v_add_f32_dpp v10, v10, v10 row_mirror row_mask:0xf bank_mask:0xf bound_ctrl:1
	s_nop 0
	v_readlane_b32 s11, v10, 16
	v_readlane_b32 s10, v10, 0
	s_nop 0
	v_mov_b32_e32 v20, s11
	v_add_f32_e32 v20, s10, v20
	v_readlane_b32 s10, v10, 32
	s_nop 1
	v_add_f32_e32 v20, s10, v20
	v_readlane_b32 s10, v10, 48
	s_nop 1
	v_add_f32_e32 v10, s10, v20
	v_mov_b32_e32 v20, 0x358637bd
	v_fmamk_f32 v10, v10, 0x3a800000, v20
	v_mul_f32_e32 v20, 0x4b800000, v10
	v_cmp_gt_f32_e32 vcc, s31, v10
	s_nop 1
	v_cndmask_b32_e32 v10, v10, v20, vcc
	v_rsq_f32_e32 v10, v10
	s_nop 0
	v_mul_f32_e32 v8, 0x45800000, v10
	v_cndmask_b32_e32 v8, v10, v8, vcc
	v_pk_mul_f32 v[20:21], v[58:59], v[8:9] op_sel_hi:[1,0]
	v_pk_mul_f32 v[22:23], v[64:65], v[8:9] op_sel_hi:[1,0]
	s_waitcnt vmcnt(0)
	v_pk_mul_f32 v[0:1], v[0:1], v[20:21]
	v_pk_mul_f32 v[20:21], v[60:61], v[8:9] op_sel_hi:[1,0]
	v_pk_mul_f32 v[16:17], v[16:17], v[8:9] op_sel_hi:[1,0]
	v_pk_mul_f32 v[2:3], v[2:3], v[20:21]
	global_store_dwordx4 v[6:7], v[0:3], off
	v_pk_mul_f32 v[20:21], v[62:63], v[8:9] op_sel_hi:[1,0]
	v_pk_mul_f32 v[18:19], v[18:19], v[8:9] op_sel_hi:[1,0]
	v_pk_mul_f32 v[240:241], v[240:241], v[20:21]
	v_pk_mul_f32 v[242:243], v[22:23], v[242:243]
	global_store_dwordx4 v[6:7], v[240:243], off offset:16
	v_pk_mul_f32 v[244:245], v[16:17], v[244:245]
	v_pk_mul_f32 v[246:247], v[18:19], v[246:247]
	global_store_dwordx4 v[6:7], v[244:247], off offset:32
	v_pk_mul_f32 v[4:5], v[12:13], v[8:9] op_sel_hi:[1,0]
	v_pk_mul_f32 v[12:13], v[14:15], v[8:9] op_sel_hi:[1,0]
	v_pk_mul_f32 v[248:249], v[4:5], v[248:249]
	v_pk_mul_f32 v[250:251], v[12:13], v[250:251]
	global_store_dwordx4 v[6:7], v[248:251], off offset:48
	s_branch .LBB0_1757
